# NSA: tile staging (ds_write pair) moved behind the step barrier and one tile further ahead, so no wave waits for its own LDS writes in front of the barrier
# baseline (speedup 1.0000x reference)
; DI float sigmoidf_(float x) { return __builtin_amdgcn_rcpf(1.0f + __expf(-x)); }
; DI void fs_reset(FState& st) { st.o0 = f16zero(); st.o1 = f16zero(); st.m = NINF; st.l = 0.f; }
; #define NSA_LOADT(it_, KR, VR) do { const int i_ = (it_); if (i_ < ntot) { const bool s_ = i_ < nsel; const int j_ = s_ ? i_ : c - (i_ - nsel); const bf16_t* p_ = sbase + (size_t)(64 * j_) * NZ; \
;         KR = *(const u32x4*)(p_ + (s_ ? ZC_KS : ZC_KW)); VR = *(const u32x4*)(p_ + (s_ ? ZC_VS : ZC_VW)); } } while (0)
; DI void nsa_task(LAS unsigned char* lds, const bf16_t* Z, const unsigned* selm, const bf16_t* OCMP, bf16_t* YA, int b, int hk, int c, int tid, int wave, int lane) {
;     ...
;     const float g_cmp = sigmoidf_(bf2f(zr[ZC_GA + head])), g_slc = sigmoidf_(bf2f(zr[ZC_GA + 8 + head])), g_win = sigmoidf_(bf2f(zr[ZC_GA + 16 + head]));
;     f32x16 y0 = f16zero(), y1 = f16zero();
;     FState st; fs_reset(st);
;     const int nsel = EN_SLC ? c + 1 : 0, nwin = EN_WIN ? (c + 1 < 9 ? c + 1 : 9) : 0, ntot = nsel + nwin;
;     const int skey = tid >> 3, sch = tid & 7;
;     const int kdst = skey * 128 + ((sch ^ ((skey >> 1) & 7)) << 4), vdst = 8192 + skey * 128 + ((sch * 16) ^ (((skey >> 1) & 1) << 6));
;     const bf16_t* sbase = Z + ((size_t)b * SEQ + skey) * NZ + hk * 64 + sch * 8;
;     u32x4 kA = {0u, 0u, 0u, 0u}, vA = kA, kB = kA, vB = kA, kC = kA, vC = kA;
;     ...
;     NSA_LOADT(0, kA, vA); NSA_LOADT(1, kB, vB); NSA_LOADT(2, kC, vC);
;     for (int it0 = 0; it0 < ntot; it0 += 3) {
;         NSA_STEP(it0, kA, vA);
;         if (it0 + 1 < ntot) NSA_STEP(it0 + 1, kB, vB);
;         if (it0 + 2 < ntot) NSA_STEP(it0 + 2, kC, vC);
;     }
.LBB0_740:
	s_waitcnt vmcnt(3)
	v_lshlrev_b32_e32 v5, 16, v5
	v_mul_f32_e32 v5, 0xbfb8aa3b, v5
	v_exp_f32_e32 v5, v5
	v_lshlrev_b32_e32 v195, 6, v4
	v_lshlrev_b32_e32 v4, 7, v194
	v_lshlrev_b32_e32 v6, 4, v205
	v_add_f32_e32 v5, 1.0, v5
	v_rcp_f32_e32 v197, v5
	v_lshlrev_b32_e32 v5, 6, v206
	v_and_b32_e32 v5, 64, v5
	v_mov_b32_e32 v16, v3
	v_mov_b32_e32 v17, v3
	v_and_or_b32 v205, v6, s66, v4
	v_lshlrev_b32_e32 v206, 4, v207
	v_lshlrev_b32_e32 v207, 4, v208
	v_lshlrev_b32_e32 v208, 4, v209
	v_lshlrev_b32_e32 v209, 4, v212
	s_add_i32 s4, s50, s69
	v_bitop3_b32 v212, v5, v4, v2 bitop3:0xde
	v_mov_b32_e32 v2, v3
	v_mov_b32_e32 v4, v3
	v_mov_b32_e32 v5, v3
	v_mov_b32_e32 v6, v3
	v_mov_b32_e32 v7, v3
	v_mov_b32_e32 v8, v3
	v_mov_b32_e32 v9, v3
	v_mov_b32_e32 v10, v3
	v_mov_b32_e32 v11, v3
	v_mov_b32_e32 v12, v3
	v_mov_b32_e32 v13, v3
	v_mov_b32_e32 v14, v3
	v_mov_b32_e32 v15, v3
	v_mov_b64_e32 v[80:81], v[16:17]
	v_mov_b64_e32 v[64:65], v[16:17]
	v_mov_b64_e32 v[48:49], v[16:17]
	v_mov_b64_e32 v[32:33], v[16:17]
	v_lshlrev_b32_e32 v194, 2, v210
	v_add_u32_e32 v210, 0xfffffe00, v190
	v_lshlrev_b32_e32 v211, 7, v211
	s_add_i32 s52, s4, -5
	s_mov_b32 s53, 0
	v_sub_u32_e32 v213, 0, v202
	s_sub_i32 s70, 0, s69
	s_add_i32 s71, s69, -2
	s_add_i32 s72, s69, -1
	v_mov_b32_e32 v214, 0
	v_mov_b32_e32 v216, 0xff800000
	s_mov_b32 s74, 0
	v_mov_b64_e32 v[78:79], v[14:15]
	v_mov_b64_e32 v[76:77], v[12:13]
	v_mov_b64_e32 v[74:75], v[10:11]
	v_mov_b64_e32 v[72:73], v[8:9]
	v_mov_b64_e32 v[70:71], v[6:7]
	v_mov_b64_e32 v[68:69], v[4:5]
	v_mov_b64_e32 v[66:67], v[2:3]
	v_mov_b64_e32 v[62:63], v[14:15]
	v_mov_b64_e32 v[60:61], v[12:13]
	v_mov_b64_e32 v[58:59], v[10:11]
	v_mov_b64_e32 v[56:57], v[8:9]
	v_mov_b64_e32 v[54:55], v[6:7]
	v_mov_b64_e32 v[52:53], v[4:5]
	v_mov_b64_e32 v[50:51], v[2:3]
	v_mov_b64_e32 v[46:47], v[14:15]
	v_mov_b64_e32 v[44:45], v[12:13]
	v_mov_b64_e32 v[42:43], v[10:11]
	v_mov_b64_e32 v[40:41], v[8:9]
	v_mov_b64_e32 v[38:39], v[6:7]
	v_mov_b64_e32 v[36:37], v[4:5]
	v_mov_b64_e32 v[34:35], v[2:3]
	v_mov_b64_e32 v[30:31], v[14:15]
	v_mov_b64_e32 v[28:29], v[12:13]
	v_mov_b64_e32 v[26:27], v[10:11]
	v_mov_b64_e32 v[24:25], v[8:9]
	v_mov_b64_e32 v[22:23], v[6:7]
	v_mov_b64_e32 v[20:21], v[4:5]
	v_mov_b64_e32 v[18:19], v[2:3]
	v_and_b32_e32 v5, 64, v198
	v_xor_b32_e32 v4, 32, v198
	v_add_u32_e32 v5, 64, v5
	v_cmp_lt_i32_e32 vcc, v4, v5
	v_cndmask_b32_e32 v4, v198, v4, vcc
	v_lshlrev_b32_e32 v215, 2, v4
	v_add3_u32 v217, v211, v203, v204
	v_add_u32_e32 v218, v217, v202
	v_add_u32_e32 v217, v217, v213
	s_waitcnt vmcnt(0)
	ds_write_b128 v205, v[162:165]
	ds_write_b128 v212, v[166:169] offset:8192
	ds_write_b128 v205, v[170:173] offset:16384
	ds_write_b128 v212, v[174:177] offset:24576
	s_cmpk_lt_u32 s51, 4
	s_cbranch_scc1 .Lnsw_pro_done
	s_mov_b32 s4, 3
	s_cmp_gt_u32 s4, s69
	s_cselect_b64 s[8:9], -1, 0
	s_add_i32 s5, s52, 2
	s_and_b64 s[8:9], s[8:9], exec
	s_cselect_b32 s4, s5, s4
	s_cselect_b32 s16, 0x1000, s65
	s_cselect_b32 s8, s64, 0x500
	s_lshl_b32 s4, s4, 6
	s_mov_b32 s9, s17
	v_mad_i64_i32 v[4:5], s[4:5], s4, v199, v[192:193]
	v_lshl_add_u64 v[6:7], v[4:5], 0, s[8:9]
	v_lshl_add_u64 v[4:5], v[4:5], 0, s[16:17]
	global_load_dwordx4 v[162:165], v[6:7], off
	global_load_dwordx4 v[166:169], v[4:5], off
	s_cmpk_lt_u32 s51, 5
	s_cbranch_scc1 .Lnsw_pro_done
	s_mov_b32 s4, 4
	s_cmp_gt_u32 s4, s69
	s_cselect_b64 s[8:9], -1, 0
	s_add_i32 s5, s52, 1
	s_and_b64 s[8:9], s[8:9], exec
	s_cselect_b32 s4, s5, s4
	s_cselect_b32 s16, 0x1000, s65
	s_cselect_b32 s8, s64, 0x500
	s_lshl_b32 s4, s4, 6
	s_mov_b32 s9, s17
	v_mad_i64_i32 v[4:5], s[4:5], s4, v199, v[192:193]
	v_lshl_add_u64 v[6:7], v[4:5], 0, s[8:9]
	v_lshl_add_u64 v[4:5], v[4:5], 0, s[16:17]
	global_load_dwordx4 v[170:173], v[6:7], off
	global_load_dwordx4 v[174:177], v[4:5], off
.Lnsw_pro_done:
	v_add_u32_e32 v221, v201, v206
	v_add_u32_e32 v222, v201, v207
	v_add_u32_e32 v223, v201, v208
	v_add_u32_e32 v224, v201, v209
	s_waitcnt lgkmcnt(0)
	s_barrier
	ds_read_b128 v[226:229], v221
	ds_read_b128 v[230:233], v221 offset:4096
	ds_read_b128 v[234:237], v222
	ds_read_b128 v[238:241], v222 offset:4096
	s_waitcnt lgkmcnt(3)
	v_mfma_f32_32x32x16_bf16 v[98:113], v[226:229], v[146:149], 0
	s_waitcnt lgkmcnt(2)
	v_mfma_f32_32x32x16_bf16 v[82:97], v[230:233], v[146:149], 0
	ds_read_b128 v[226:229], v223
	ds_read_b128 v[230:233], v223 offset:4096
	s_waitcnt lgkmcnt(3)
	v_mfma_f32_32x32x16_bf16 v[98:113], v[234:237], v[150:153], v[98:113]
	s_waitcnt lgkmcnt(2)
	v_mfma_f32_32x32x16_bf16 v[82:97], v[238:241], v[150:153], v[82:97]
	ds_read_b128 v[234:237], v224
	ds_read_b128 v[238:241], v224 offset:4096
	s_waitcnt lgkmcnt(3)
	v_mfma_f32_32x32x16_bf16 v[98:113], v[226:229], v[154:157], v[98:113]
	s_waitcnt lgkmcnt(2)
	v_mfma_f32_32x32x16_bf16 v[82:97], v[230:233], v[154:157], v[82:97]
	s_waitcnt lgkmcnt(1)
	v_mfma_f32_32x32x16_bf16 v[98:113], v[234:237], v[158:161], v[98:113]
	s_waitcnt lgkmcnt(0)
	v_mfma_f32_32x32x16_bf16 v[82:97], v[238:241], v[158:161], v[82:97]
.LBB0_741:
	s_mov_b32 s76, 0
	s_add_i32 s73, s74, 3
	s_cmp_ge_u32 s73, s51
	s_cselect_b64 s[6:7], -1, 0
	s_waitcnt lgkmcnt(0)
	s_barrier
	s_waitcnt vmcnt(1)
	ds_write_b128 v205, v[182:185] offset:32768
	s_waitcnt vmcnt(0)
	ds_write_b128 v212, v[178:181] offset:40960
	s_add_i32 s4, s74, 5
	s_cmp_ge_u32 s4, s51
	s_cbranch_scc1 .LBB0_743
	s_cmp_gt_u32 s4, s69
	s_cselect_b64 s[8:9], -1, 0
	s_mov_b32 s5, s52
	s_and_b64 s[8:9], s[8:9], exec
	s_cselect_b32 s4, s5, s4
	s_cselect_b32 s16, 0x1000, s65
	s_cselect_b32 s8, s64, 0x500
	s_lshl_b32 s4, s4, 6
	s_mov_b32 s9, s17
	v_mad_i64_i32 v[4:5], s[4:5], s4, v199, v[192:193]
	v_lshl_add_u64 v[6:7], v[4:5], 0, s[8:9]
	v_lshl_add_u64 v[4:5], v[4:5], 0, s[16:17]
	global_load_dwordx4 v[182:185], v[6:7], off
	global_load_dwordx4 v[178:181], v[4:5], off

; #define LAS __attribute__((address_space(3)))
; #define MFMA32(a, b, c) __builtin_amdgcn_mfma_f32_32x32x16_bf16((a), (b), (c), 0, 0, 0)
; DI float fexp2(float x) { return __builtin_amdgcn_exp2f(x); }
; DI s16x4 vtr(const LAS unsigned char* p) { return __builtin_bit_cast(s16x4, __builtin_amdgcn_ds_read_tr16_b64_v4i16((LAS v4i16_t*)p)); }
; DI void flash_pv(FState& st, f32x16& p0, f32x16& p1, bool rowon, const LAS unsigned char* vb, int lane) {
;     ...
;     const float cl = rowon ? SM_C : 0.0f;
;     const float bl = rowon ? ((st.m == NINF) ? 0.0f : -st.m * SM_C) : NINF;
;     float sum = 0.f;
; #pragma unroll
;     for (int r = 0; r < 16; ++r) { p0[r] = fexp2(__builtin_fmaf(p0[r], cl, bl)); p1[r] = fexp2(__builtin_fmaf(p1[r], cl, bl)); sum += p0[r] + p1[r]; }
;     st.l += sum;
;     const int h = lane >> 5;
;     const int vx = (((lane & 15) >> 3) & 1) * 64;
;     const LAS unsigned char* vp = vb + (4 * h + ((lane & 15) >> 2)) * 128 + ((lane >> 4) & 1) * 32 + (lane & 3) * 8;
; #pragma unroll
;     for (int sub = 0; sub < 2; ++sub)
; #pragma unroll
;         for (int s2 = 0; s2 < 2; ++s2) {
;             const bf16x8 pf = pack8h(sub ? p1 : p0, s2);
;             const LAS unsigned char* vq = vp + (32 * sub + 16 * s2) * 128;
;             { const s16x4 lo = vtr(vq + vx), hi = vtr(vq + 1024 + vx); const bf16x8 vf = {lo[0], lo[1], lo[2], lo[3], hi[0], hi[1], hi[2], hi[3]}; st.o0 = MFMA32(vf, pf, st.o0); }
;             { const s16x4 lo = vtr(vq + (64 - vx)), hi = vtr(vq + 1024 + (64 - vx)); const bf16x8 vf = {lo[0], lo[1], lo[2], lo[3], hi[0], hi[1], hi[2], hi[3]}; st.o1 = MFMA32(vf, pf, st.o1); }
;         }
.LBB0_759:
	s_or_b64 exec, exec, s[4:5]
	v_fma_f32 v2, v98, v5, v4
	v_exp_f32_e32 v12, v2
	v_fma_f32 v2, v82, v5, v4
	v_exp_f32_e32 v246, v2
	s_waitcnt lgkmcnt(3)
	v_mfma_f32_32x32x16_bf16 v[130:145], v[226:229], v[154:157], v[130:145]
	v_fma_f32 v2, v99, v5, v4
	v_exp_f32_e32 v6, v2
	v_fma_f32 v2, v83, v5, v4
	v_exp_f32_e32 v2, v2
	v_add_f32_e32 v7, v12, v246
	s_add_i32 s77, s74, 1
	s_cmp_ge_u32 s77, s51
	v_pk_add_f32 v[8:9], v[6:7], v[2:3]
	v_fma_f32 v7, v100, v5, v4
	v_add_f32_e32 v99, v8, v9
	s_waitcnt lgkmcnt(2)
	v_mfma_f32_32x32x16_bf16 v[114:129], v[230:233], v[154:157], v[114:129]
	v_fma_f32 v8, v84, v5, v4
	v_exp_f32_e32 v7, v7
	v_exp_f32_e32 v247, v8
	v_fma_f32 v8, v101, v5, v4
	v_fma_f32 v9, v85, v5, v4
	v_exp_f32_e32 v8, v8
	v_exp_f32_e32 v98, v9
	v_add_f32_e32 v9, v7, v247
	v_cvt_pk_bf16_f32 v6, v12, v6
	v_cvt_pk_bf16_f32 v7, v7, v8
	s_waitcnt lgkmcnt(1)
	v_mfma_f32_32x32x16_bf16 v[130:145], v[234:237], v[158:161], v[130:145]
	v_pk_add_f32 v[10:11], v[8:9], v[98:99]
	v_fma_f32 v9, v102, v5, v4
	v_add_f32_e32 v101, v10, v11
	v_fma_f32 v10, v86, v5, v4
	v_exp_f32_e32 v99, v10
	v_fma_f32 v10, v103, v5, v4
	v_exp_f32_e32 v9, v9
	v_exp_f32_e32 v14, v10
	v_fma_f32 v10, v87, v5, v4
	v_exp_f32_e32 v100, v10
	s_waitcnt lgkmcnt(0)
	v_mfma_f32_32x32x16_bf16 v[114:129], v[238:241], v[158:161], v[114:129]
	v_add_f32_e32 v15, v9, v99
	v_cvt_pk_bf16_f32 v8, v9, v14
	v_pk_add_f32 v[10:11], v[14:15], v[100:101]
	s_nop 0
	v_add_f32_e32 v87, v10, v11
	v_fma_f32 v10, v104, v5, v4
	v_exp_f32_e32 v15, v10
	v_fma_f32 v10, v88, v5, v4
	v_exp_f32_e32 v101, v10
	v_fma_f32 v10, v105, v5, v4
	v_exp_f32_e32 v16, v10
	v_fma_f32 v10, v89, v5, v4
	v_exp_f32_e32 v86, v10
	v_add_f32_e32 v17, v15, v101
	v_cvt_pk_bf16_f32 v9, v15, v16
	v_pk_add_f32 v[10:11], v[16:17], v[86:87]
	s_nop 0
	v_add_f32_e32 v89, v10, v11
	v_fma_f32 v10, v106, v5, v4
	v_exp_f32_e32 v87, v10
	v_fma_f32 v10, v90, v5, v4
	v_exp_f32_e32 v248, v10
	v_fma_f32 v10, v107, v5, v4
	v_exp_f32_e32 v90, v10
	v_fma_f32 v10, v91, v5, v4
	v_exp_f32_e32 v88, v10
	v_fma_f32 v10, v108, v5, v4
	v_exp_f32_e32 v107, v10
	v_fma_f32 v10, v92, v5, v4
	v_add_f32_e32 v91, v87, v248
	v_exp_f32_e32 v108, v10
	v_pk_add_f32 v[10:11], v[90:91], v[88:89]
	v_fma_f32 v91, v112, v5, v4
	v_add_f32_e32 v103, v10, v11
	v_fma_f32 v10, v109, v5, v4
	v_exp_f32_e32 v104, v10
	v_fma_f32 v10, v93, v5, v4
	v_exp_f32_e32 v102, v10
	ds_read_b64_tr_b16 v[10:11], v218 offset:8192
	ds_read_b64_tr_b16 v[12:13], v218 offset:9216
	ds_read_b64_tr_b16 v[14:15], v217 offset:8256
	ds_read_b64_tr_b16 v[16:17], v217 offset:9280
	ds_read_b64_tr_b16 v[82:83], v218 offset:10240
	ds_read_b64_tr_b16 v[84:85], v218 offset:11264
	s_waitcnt lgkmcnt(4)
	v_mfma_f32_32x32x16_bf16 v[66:81], v[10:13], v[6:9], v[66:81]
	v_fma_f32 v10, v110, v5, v4
	v_exp_f32_e32 v89, v10
	v_fma_f32 v10, v111, v5, v4
	v_exp_f32_e32 v92, v10
	v_exp_f32_e32 v109, v91
	v_add_f32_e32 v105, v107, v108
	ds_read_b64_tr_b16 v[10:11], v217 offset:10304
	ds_read_b64_tr_b16 v[12:13], v217 offset:11328
	s_waitcnt lgkmcnt(4)
	v_mfma_f32_32x32x16_bf16 v[50:65], v[14:17], v[6:9], v[50:65]
	v_fma_f32 v6, v113, v5, v4
	v_exp_f32_e32 v106, v6
	v_cvt_pk_bf16_f32 v6, v87, v90
	v_cvt_pk_bf16_f32 v7, v107, v104
	v_cvt_pk_bf16_f32 v8, v89, v92
	v_cvt_pk_bf16_f32 v9, v109, v106
	v_pk_add_f32 v[14:15], v[104:105], v[102:103]
	s_waitcnt lgkmcnt(2)
	v_mfma_f32_32x32x16_bf16 v[66:81], v[82:85], v[6:9], v[66:81]
	v_add_f32_e64 v91, v14, v15
	v_fma_f32 v14, v94, v5, v4
	v_exp_f32_e32 v94, v14
	ds_read_b64_tr_b16 v[14:15], v218 offset:12288
	ds_read_b64_tr_b16 v[16:17], v218 offset:13312
	v_fma_f32 v82, v95, v5, v4
	v_exp_f32_e32 v90, v82
	v_add_f32_e32 v93, v89, v94
	s_waitcnt lgkmcnt(2)
	v_mfma_f32_32x32x16_bf16 v[50:65], v[10:13], v[6:9], v[50:65]
	v_cvt_pk_bf16_f32 v6, v246, v2
	v_cvt_pk_bf16_f32 v7, v247, v98
	v_cvt_pk_bf16_f32 v8, v99, v100
	v_cvt_pk_bf16_f32 v9, v101, v86
	ds_read_b64_tr_b16 v[10:11], v218 offset:14336
	ds_read_b64_tr_b16 v[12:13], v218 offset:15360
	v_pk_add_f32 v[82:83], v[92:93], v[90:91]
	v_fma_f32 v2, v96, v5, v4
	s_waitcnt lgkmcnt(2)
	v_mfma_f32_32x32x16_bf16 v[66:81], v[14:17], v[6:9], v[66:81]
	ds_read_b64_tr_b16 v[14:15], v217 offset:12352
	ds_read_b64_tr_b16 v[16:17], v217 offset:13376
	v_add_f32_e64 v87, v82, v83
	v_fmac_f32_e32 v4, v97, v5
	ds_read_b64_tr_b16 v[82:83], v217 offset:14400
	ds_read_b64_tr_b16 v[84:85], v217 offset:15424
	v_exp_f32_e32 v2, v2
	v_exp_f32_e32 v86, v4
	v_cvt_pk_bf16_f32 v4, v248, v88
	s_waitcnt lgkmcnt(2)
	v_mfma_f32_32x32x16_bf16 v[50:65], v[14:17], v[6:9], v[50:65]
	v_cvt_pk_bf16_f32 v5, v108, v102
	v_cvt_pk_bf16_f32 v6, v94, v90
	v_cvt_pk_bf16_f32 v7, v2, v86
	v_add_f32_e32 v107, v109, v2
	v_add_f32_e64 v8, v106, v86
	v_add_f32_e64 v9, v107, v87
	v_add_f32_e32 v2, v8, v9
	v_mfma_f32_32x32x16_bf16 v[66:81], v[10:13], v[4:7], v[66:81]
	v_add_f32_e32 v214, v214, v2
	s_waitcnt lgkmcnt(0)
	v_mfma_f32_32x32x16_bf16 v[50:65], v[82:85], v[4:7], v[50:65]
	s_cbranch_scc1 .LBB0_780
	s_movk_i32 s76, 0x4000
	s_waitcnt lgkmcnt(0)
	s_barrier
	s_waitcnt vmcnt(1)
	ds_write_b128 v205, v[162:165]
	s_waitcnt vmcnt(0)
	ds_write_b128 v212, v[166:169] offset:8192
	s_add_i32 s4, s74, 6
	s_cmp_ge_u32 s4, s51
	s_cbranch_scc1 .LBB0_762
	s_cmp_gt_u32 s4, s69
	s_cselect_b64 s[8:9], -1, 0
	s_add_i32 s5, s52, -1
	s_and_b64 s[8:9], s[8:9], exec
	s_cselect_b32 s4, s5, s4
	s_cselect_b32 s16, 0x1000, s65
	s_cselect_b32 s8, s64, 0x500
	s_lshl_b32 s4, s4, 6
	s_mov_b32 s9, s17
	v_mad_i64_i32 v[4:5], s[4:5], s4, v199, v[192:193]
	v_lshl_add_u64 v[6:7], v[4:5], 0, s[8:9]
	v_lshl_add_u64 v[4:5], v[4:5], 0, s[16:17]
	global_load_dwordx4 v[162:165], v[6:7], off
	global_load_dwordx4 v[166:169], v[4:5], off

.LBB0_781:
	s_waitcnt lgkmcnt(0)
	s_barrier
	s_waitcnt vmcnt(1)
	ds_write_b128 v205, v[170:173] offset:16384
	s_waitcnt vmcnt(0)
	ds_write_b128 v212, v[174:177] offset:24576
	s_add_i32 s4, s74, 7
	s_cmp_ge_u32 s4, s51
	s_cbranch_scc1 .LBB0_783
	s_cmp_gt_u32 s4, s69
	s_cselect_b64 s[8:9], -1, 0
	s_add_i32 s5, s52, -2
	s_and_b64 s[8:9], s[8:9], exec
	s_cselect_b32 s4, s5, s4
	s_cselect_b32 s16, 0x1000, s65
	s_cselect_b32 s8, s64, 0x500
	s_lshl_b32 s4, s4, 6
	s_mov_b32 s9, s17
	v_mad_i64_i32 v[4:5], s[4:5], s4, v199, v[192:193]
	v_lshl_add_u64 v[6:7], v[4:5], 0, s[8:9]
	v_lshl_add_u64 v[4:5], v[4:5], 0, s[16:17]
	global_load_dwordx4 v[170:173], v[6:7], off
	global_load_dwordx4 v[174:177], v[4:5], off

; #define LAS __attribute__((address_space(3)))
; #define MFMA32(a, b, c) __builtin_amdgcn_mfma_f32_32x32x16_bf16((a), (b), (c), 0, 0, 0)
; DI float fexp2(float x) { return __builtin_amdgcn_exp2f(x); }
; DI s16x4 vtr(const LAS unsigned char* p) { return __builtin_bit_cast(s16x4, __builtin_amdgcn_ds_read_tr16_b64_v4i16((LAS v4i16_t*)p)); }
; DI void flash_pv(FState& st, f32x16& p0, f32x16& p1, bool rowon, const LAS unsigned char* vb, int lane) {
;     ...
;     const float cl = rowon ? SM_C : 0.0f;
;     const float bl = rowon ? ((st.m == NINF) ? 0.0f : -st.m * SM_C) : NINF;
;     float sum = 0.f;
; #pragma unroll
;     for (int r = 0; r < 16; ++r) { p0[r] = fexp2(__builtin_fmaf(p0[r], cl, bl)); p1[r] = fexp2(__builtin_fmaf(p1[r], cl, bl)); sum += p0[r] + p1[r]; }
;     st.l += sum;
;     const int h = lane >> 5;
;     const int vx = (((lane & 15) >> 3) & 1) * 64;
;     const LAS unsigned char* vp = vb + (4 * h + ((lane & 15) >> 2)) * 128 + ((lane >> 4) & 1) * 32 + (lane & 3) * 8;
; #pragma unroll
;     for (int sub = 0; sub < 2; ++sub)
; #pragma unroll
;         for (int s2 = 0; s2 < 2; ++s2) {
;             const bf16x8 pf = pack8h(sub ? p1 : p0, s2);
;             const LAS unsigned char* vq = vp + (32 * sub + 16 * s2) * 128;
;             { const s16x4 lo = vtr(vq + vx), hi = vtr(vq + 1024 + vx); const bf16x8 vf = {lo[0], lo[1], lo[2], lo[3], hi[0], hi[1], hi[2], hi[3]}; st.o0 = MFMA32(vf, pf, st.o0); }
;             { const s16x4 lo = vtr(vq + (64 - vx)), hi = vtr(vq + 1024 + (64 - vx)); const bf16x8 vf = {lo[0], lo[1], lo[2], lo[3], hi[0], hi[1], hi[2], hi[3]}; st.o1 = MFMA32(vf, pf, st.o1); }
;         }
.Lnq_759:
	s_or_b64 exec, exec, s[4:5]
	v_fma_f32 v2, v130, v5, v4
	v_exp_f32_e32 v12, v2
	v_fma_f32 v2, v114, v5, v4
	v_exp_f32_e32 v246, v2
	s_waitcnt lgkmcnt(3)
	v_mfma_f32_32x32x16_bf16 v[98:113], v[226:229], v[154:157], v[98:113]
	v_fma_f32 v2, v131, v5, v4
	v_exp_f32_e32 v6, v2
	v_fma_f32 v2, v115, v5, v4
	v_exp_f32_e32 v2, v2
	v_add_f32_e32 v7, v12, v246
	s_add_i32 s77, s74, 1
	s_cmp_ge_u32 s77, s51
	v_pk_add_f32 v[8:9], v[6:7], v[2:3]
	v_fma_f32 v7, v132, v5, v4
	v_add_f32_e32 v131, v8, v9
	s_waitcnt lgkmcnt(2)
	v_mfma_f32_32x32x16_bf16 v[82:97], v[230:233], v[154:157], v[82:97]
	v_fma_f32 v8, v116, v5, v4
	v_exp_f32_e32 v7, v7
	v_exp_f32_e32 v247, v8
	v_fma_f32 v8, v133, v5, v4
	v_fma_f32 v9, v117, v5, v4
	v_exp_f32_e32 v8, v8
	v_exp_f32_e32 v130, v9
	v_add_f32_e32 v9, v7, v247
	v_cvt_pk_bf16_f32 v6, v12, v6
	v_cvt_pk_bf16_f32 v7, v7, v8
	s_waitcnt lgkmcnt(1)
	v_mfma_f32_32x32x16_bf16 v[98:113], v[234:237], v[158:161], v[98:113]
	v_pk_add_f32 v[10:11], v[8:9], v[130:131]
	v_fma_f32 v9, v134, v5, v4
	v_add_f32_e32 v133, v10, v11
	v_fma_f32 v10, v118, v5, v4
	v_exp_f32_e32 v131, v10
	v_fma_f32 v10, v135, v5, v4
	v_exp_f32_e32 v9, v9
	v_exp_f32_e32 v14, v10
	v_fma_f32 v10, v119, v5, v4
	v_exp_f32_e32 v132, v10
	s_waitcnt lgkmcnt(0)
	v_mfma_f32_32x32x16_bf16 v[82:97], v[238:241], v[158:161], v[82:97]
	v_add_f32_e32 v15, v9, v131
	v_cvt_pk_bf16_f32 v8, v9, v14
	v_pk_add_f32 v[10:11], v[14:15], v[132:133]
	s_nop 0
	v_add_f32_e32 v119, v10, v11
	v_fma_f32 v10, v136, v5, v4
	v_exp_f32_e32 v15, v10
	v_fma_f32 v10, v120, v5, v4
	v_exp_f32_e32 v133, v10
	v_fma_f32 v10, v137, v5, v4
	v_exp_f32_e32 v16, v10
	v_fma_f32 v10, v121, v5, v4
	v_exp_f32_e32 v118, v10
	v_add_f32_e32 v17, v15, v133
	v_cvt_pk_bf16_f32 v9, v15, v16
	v_pk_add_f32 v[10:11], v[16:17], v[118:119]
	s_nop 0
	v_add_f32_e32 v121, v10, v11
	v_fma_f32 v10, v138, v5, v4
	v_exp_f32_e32 v119, v10
	v_fma_f32 v10, v122, v5, v4
	v_exp_f32_e32 v248, v10
	v_fma_f32 v10, v139, v5, v4
	v_exp_f32_e32 v122, v10
	v_fma_f32 v10, v123, v5, v4
	v_exp_f32_e32 v120, v10
	v_fma_f32 v10, v140, v5, v4
	v_exp_f32_e32 v139, v10
	v_fma_f32 v10, v124, v5, v4
	v_add_f32_e32 v123, v119, v248
	v_exp_f32_e32 v140, v10
	v_pk_add_f32 v[10:11], v[122:123], v[120:121]
	v_fma_f32 v123, v144, v5, v4
	v_add_f32_e32 v135, v10, v11
	v_fma_f32 v10, v141, v5, v4
	v_exp_f32_e32 v136, v10
	v_fma_f32 v10, v125, v5, v4
	v_exp_f32_e32 v134, v10
	ds_read_b64_tr_b16 v[10:11], v218 offset:8192
	ds_read_b64_tr_b16 v[12:13], v218 offset:9216
	ds_read_b64_tr_b16 v[14:15], v217 offset:8256
	ds_read_b64_tr_b16 v[16:17], v217 offset:9280
	ds_read_b64_tr_b16 v[114:115], v218 offset:10240
	ds_read_b64_tr_b16 v[116:117], v218 offset:11264
	s_waitcnt lgkmcnt(4)
	v_mfma_f32_32x32x16_bf16 v[66:81], v[10:13], v[6:9], v[66:81]
	v_fma_f32 v10, v142, v5, v4
	v_exp_f32_e32 v121, v10
	v_fma_f32 v10, v143, v5, v4
	v_exp_f32_e32 v124, v10
	v_exp_f32_e32 v141, v123
	v_add_f32_e32 v137, v139, v140
	ds_read_b64_tr_b16 v[10:11], v217 offset:10304
	ds_read_b64_tr_b16 v[12:13], v217 offset:11328
	s_waitcnt lgkmcnt(4)
	v_mfma_f32_32x32x16_bf16 v[50:65], v[14:17], v[6:9], v[50:65]
	v_fma_f32 v6, v145, v5, v4
	v_exp_f32_e32 v138, v6
	v_cvt_pk_bf16_f32 v6, v119, v122
	v_cvt_pk_bf16_f32 v7, v139, v136
	v_cvt_pk_bf16_f32 v8, v121, v124
	v_cvt_pk_bf16_f32 v9, v141, v138
	v_pk_add_f32 v[14:15], v[136:137], v[134:135]
	s_waitcnt lgkmcnt(2)
	v_mfma_f32_32x32x16_bf16 v[66:81], v[114:117], v[6:9], v[66:81]
	v_add_f32_e64 v123, v14, v15
	v_fma_f32 v14, v126, v5, v4
	v_exp_f32_e32 v126, v14
	ds_read_b64_tr_b16 v[14:15], v218 offset:12288
	ds_read_b64_tr_b16 v[16:17], v218 offset:13312
	v_fma_f32 v114, v127, v5, v4
	v_exp_f32_e32 v122, v114
	v_add_f32_e32 v125, v121, v126
	s_waitcnt lgkmcnt(2)
	v_mfma_f32_32x32x16_bf16 v[50:65], v[10:13], v[6:9], v[50:65]
	v_cvt_pk_bf16_f32 v6, v246, v2
	v_cvt_pk_bf16_f32 v7, v247, v130
	v_cvt_pk_bf16_f32 v8, v131, v132
	v_cvt_pk_bf16_f32 v9, v133, v118
	ds_read_b64_tr_b16 v[10:11], v218 offset:14336
	ds_read_b64_tr_b16 v[12:13], v218 offset:15360
	v_pk_add_f32 v[114:115], v[124:125], v[122:123]
	v_fma_f32 v2, v128, v5, v4
	s_waitcnt lgkmcnt(2)
	v_mfma_f32_32x32x16_bf16 v[66:81], v[14:17], v[6:9], v[66:81]
	ds_read_b64_tr_b16 v[14:15], v217 offset:12352
	ds_read_b64_tr_b16 v[16:17], v217 offset:13376
	v_add_f32_e64 v119, v114, v115
	v_fmac_f32_e32 v4, v129, v5
	ds_read_b64_tr_b16 v[114:115], v217 offset:14400
	ds_read_b64_tr_b16 v[116:117], v217 offset:15424
	v_exp_f32_e32 v2, v2
	v_exp_f32_e32 v118, v4
	v_cvt_pk_bf16_f32 v4, v248, v120
	s_waitcnt lgkmcnt(2)
	v_mfma_f32_32x32x16_bf16 v[50:65], v[14:17], v[6:9], v[50:65]
	v_cvt_pk_bf16_f32 v5, v140, v134
	v_cvt_pk_bf16_f32 v6, v126, v122
	v_cvt_pk_bf16_f32 v7, v2, v118
	v_add_f32_e32 v139, v141, v2
	v_add_f32_e64 v8, v138, v118
	v_add_f32_e64 v9, v139, v119
	v_add_f32_e32 v2, v8, v9
	v_mfma_f32_32x32x16_bf16 v[66:81], v[10:13], v[4:7], v[66:81]
	v_add_f32_e32 v214, v214, v2
	s_waitcnt lgkmcnt(0)
	v_mfma_f32_32x32x16_bf16 v[50:65], v[114:117], v[4:7], v[50:65]
	s_cbranch_scc1 .Lnq_780
	s_movk_i32 s76, 0x4000
	s_waitcnt lgkmcnt(0)
	s_barrier
	s_waitcnt vmcnt(1)
	ds_write_b128 v205, v[162:165]
	s_waitcnt vmcnt(0)
	ds_write_b128 v212, v[166:169] offset:8192
	s_add_i32 s4, s74, 6
	s_cmp_ge_u32 s4, s51
	s_cbranch_scc1 .Lnq_762
	s_cmp_gt_u32 s4, s69
	s_cselect_b64 s[8:9], -1, 0
	s_add_i32 s5, s52, -1
	s_and_b64 s[8:9], s[8:9], exec
	s_cselect_b32 s4, s5, s4
	s_cselect_b32 s16, 0x1000, s65
	s_cselect_b32 s8, s64, 0x500
	s_lshl_b32 s4, s4, 6
	s_mov_b32 s9, s17
	v_mad_i64_i32 v[4:5], s[4:5], s4, v199, v[192:193]
	v_lshl_add_u64 v[6:7], v[4:5], 0, s[8:9]
	v_lshl_add_u64 v[4:5], v[4:5], 0, s[16:17]
	global_load_dwordx4 v[162:165], v[6:7], off
	global_load_dwordx4 v[166:169], v[4:5], off
